# v29 + EpiUp's lane ids / addresses / conv-weight loads moved in front of the unit's closing barrier (the loads fly under it)
# speedup vs baseline: 1.0149x; 1.0013x over previous
; template <class Epi, class Sched, bool ALIGN_EPI = false, bool SP2 = false>
; __device__ __forceinline__ void gemm_phase(PG8_LAS unsigned char* lds, const int Kdim  , const int Klen  , const Sched& S, const Epi& E, const int wave_s) {
;     ...
;         if constexpr (ALIGN_EPI) { if (wr == 0) PG8_BAR; }
;         if constexpr (!Epi::AFTER_DRAIN) { E(acc, cur, wr, wc, fr, fq); S.done(cur); }
;     __device__ __forceinline__ void operator()(pg8::f32x4 (&acc)[2][2][4][2], const pg8::Unit& u, int wr_, int wc_, int fr_, int fq_) const {
;         int t_ = tid_from(wr_ * 4 + wc_); asm volatile("" : "+v"(t_));
;         const int fr = t_ & 15, fq = (t_ >> 4) & 3, wc = (t_ >> 6) & 3, wr = t_ >> 8; (void)wr_; (void)wc_; (void)fr_; (void)fq_;
;         const unsigned hc0 = (unsigned)(u.pn * 128 + wc * 32 + 8 * fq);
;         const bool e0 = fr == 0, e3 = fr == 15;
;         __builtin_amdgcn_sched_barrier(0);
; #pragma unroll
;         for (int ai = 0; ai < 2; ++ai) {
;             const int rbase = u.pm * 256 + ai * 128 + wr * 64;
;             const unsigned eb0 = (unsigned)((rbase >> 6) << 1) * (unsigned)DFF, eb3 = eb0 + (unsigned)DFF;
; #pragma unroll
;             for (int n = 0; n < 2; ++n) {
;                 const unsigned hc = hc0 + 4u * (unsigned)n;
;                 const pg8::f32x4 w0 = *(const GAS pg8::f32x4*)&cw[hc], w1 = *(const GAS pg8::f32x4*)&cw[(unsigned)DFF + hc], w2 = *(const GAS pg8::f32x4*)&cw[2u * (unsigned)DFF + hc], bb = *(const GAS pg8::f32x4*)&cb[hc];
;                 if (e0) { *(GAS pg8::f32x4*)&EG[eb0 + hc] = acc[ai][0][0][n]; *(GAS pg8::f32x4*)&EU[eb0 + hc] = acc[ai][1][0][n]; }
;                 if (e3) { *(GAS pg8::f32x4*)&EG[eb3 + hc] = acc[ai][0][3][n]; *(GAS pg8::f32x4*)&EU[eb3 + hc] = acc[ai][1][3][n]; }
; #pragma unroll
;                 for (int j = 0; j < 4; ++j) {
;                     float pr[4], nx[4], gg[4];
; #pragma unroll
;                     for (int m = 0; m < 4; ++m) { gg[m] = acc[ai][0][m][n][j]; pr[m] = dpp_ror<0x121>(gg[m]); nx[m] = dpp_ror<0x12F>(gg[m]); }
; #pragma unroll
;                     for (int m = 0; m < 4; ++m) {
;                         const float pv = fr > 0 ? pr[m] : (m > 0 ? pr[m > 0 ? m - 1 : 0] : 0.f);
;                         const float nv = fr < 15 ? nx[m] : (m < 3 ? nx[m < 3 ? m + 1 : 3] : 0.f);
;                         const float cv = w0[j] * pv + w1[j] * gg[m] + w2[j] * nv + bb[j];
.Lkdone_3:
	s_mov_b32 s92, s57
	s_mov_b32 s57, s94
	s_mov_b32 s93, s52
	v_mbcnt_lo_u32_b32 v235, -1, 0
	v_mbcnt_hi_u32_b32 v235, -1, v235
	v_mov_b32_e32 v172, 0xc0135761
	v_or_b32_e32 v235, s75, v235
	v_mov_b32_e32 v173, 0xc0135761
	v_and_b32_e32 v248, 15, v235
	v_lshrrev_b32_e32 v176, 1, v235
	v_ashrrev_i32_e32 v249, 2, v235
	v_and_b32_e32 v176, 0x78, v176
	v_and_b32_e32 v249, 0xffffffc0, v249
	v_lshl_or_b32 v176, s10, 7, v176
	v_lshl_add_u32 v249, s8, 8, v249
	v_cmp_eq_u32_e64 s[12:13], 0, v248
	v_cmp_eq_u32_e64 s[30:31], 15, v248
	v_cmp_ne_u32_e64 s[10:11], 0, v248
	v_cmp_ne_u32_e64 s[62:63], 15, v248
	v_add_u32_e32 v233, v249, v248
	v_lshrrev_b32_e32 v232, 5, v249
	s_movk_i32 s8, 0x1600
	v_mul_lo_u32 v233, v233, s8
	v_mul_lo_u32 v232, v232, s8
	v_add_u32_e32 v233, v233, v176
	v_add_u32_e32 v232, v232, v176
	v_lshlrev_b32_e32 v176, 2, v176
	v_lshlrev_b32_e32 v233, 1, v233
	v_lshlrev_b32_e32 v232, 2, v232
	v_add_u32_e32 v218, 0x5800, v176
	v_add_u32_e32 v219, 0xb000, v176
	global_load_dwordx4 v[120:123], v176, s[24:25] offset:0
	global_load_dwordx4 v[124:127], v218, s[24:25] offset:0
	global_load_dwordx4 v[128:131], v219, s[24:25] offset:0
	global_load_dwordx4 v[132:135], v176, s[26:27] offset:0
	global_load_dwordx4 v[178:181], v176, s[24:25] offset:16
	global_load_dwordx4 v[182:185], v218, s[24:25] offset:16
	global_load_dwordx4 v[186:189], v219, s[24:25] offset:16
	global_load_dwordx4 v[190:193], v176, s[26:27] offset:16
	v_mov_b32_e32 v174, 0xbdd2d3e7
	v_mov_b32_e32 v175, 0xbdd2d3e7
	v_mov_b32_e32 v210, 1.0
	v_mov_b32_e32 v211, 1.0
	s_mov_b64 s[8:9], exec
	s_and_b64 vcc, exec, s[34:35]
	s_cbranch_vccz .LBB0_1454
	s_barrier
.LBB0_1454:
	s_waitcnt vmcnt(0)
	v_pk_fma_f32 v[194:195], v[124:125], v[140:141], v[132:133]
	v_pk_fma_f32 v[196:197], v[126:127], v[142:143], v[134:135]
	v_pk_fma_f32 v[198:199], v[124:125], v[84:85], v[132:133]
	v_pk_fma_f32 v[200:201], v[126:127], v[86:87], v[134:135]
	v_pk_fma_f32 v[202:203], v[124:125], v[80:81], v[132:133]
	v_pk_fma_f32 v[204:205], v[126:127], v[82:83], v[134:135]
	v_pk_fma_f32 v[206:207], v[124:125], v[136:137], v[132:133]
	v_pk_fma_f32 v[208:209], v[126:127], v[138:139], v[134:135]
	v_fmac_f32_dpp v194, v140, v120 row_shr:1 row_mask:0xf bank_mask:0xf
	v_fmac_f32_dpp v195, v141, v121 row_shr:1 row_mask:0xf bank_mask:0xf
	v_fmac_f32_dpp v196, v142, v122 row_shr:1 row_mask:0xf bank_mask:0xf
	v_fmac_f32_dpp v197, v143, v123 row_shr:1 row_mask:0xf bank_mask:0xf
	v_fmac_f32_dpp v198, v84, v120 row_shr:1 row_mask:0xf bank_mask:0xf
	v_fmac_f32_dpp v199, v85, v121 row_shr:1 row_mask:0xf bank_mask:0xf
	v_fmac_f32_dpp v200, v86, v122 row_shr:1 row_mask:0xf bank_mask:0xf
	v_fmac_f32_dpp v201, v87, v123 row_shr:1 row_mask:0xf bank_mask:0xf
	v_fmac_f32_dpp v202, v80, v120 row_shr:1 row_mask:0xf bank_mask:0xf
	v_fmac_f32_dpp v203, v81, v121 row_shr:1 row_mask:0xf bank_mask:0xf
	v_fmac_f32_dpp v204, v82, v122 row_shr:1 row_mask:0xf bank_mask:0xf
	v_fmac_f32_dpp v205, v83, v123 row_shr:1 row_mask:0xf bank_mask:0xf
	v_fmac_f32_dpp v206, v136, v120 row_shr:1 row_mask:0xf bank_mask:0xf
	v_fmac_f32_dpp v207, v137, v121 row_shr:1 row_mask:0xf bank_mask:0xf
	v_fmac_f32_dpp v208, v138, v122 row_shr:1 row_mask:0xf bank_mask:0xf
	v_fmac_f32_dpp v209, v139, v123 row_shr:1 row_mask:0xf bank_mask:0xf
	v_fmac_f32_dpp v194, v140, v128 row_shl:1 row_mask:0xf bank_mask:0xf
	v_fmac_f32_dpp v195, v141, v129 row_shl:1 row_mask:0xf bank_mask:0xf
	v_fmac_f32_dpp v196, v142, v130 row_shl:1 row_mask:0xf bank_mask:0xf
	v_fmac_f32_dpp v197, v143, v131 row_shl:1 row_mask:0xf bank_mask:0xf
	v_fmac_f32_dpp v198, v84, v128 row_shl:1 row_mask:0xf bank_mask:0xf
	v_fmac_f32_dpp v199, v85, v129 row_shl:1 row_mask:0xf bank_mask:0xf
	v_fmac_f32_dpp v200, v86, v130 row_shl:1 row_mask:0xf bank_mask:0xf
	v_fmac_f32_dpp v201, v87, v131 row_shl:1 row_mask:0xf bank_mask:0xf
	v_fmac_f32_dpp v202, v80, v128 row_shl:1 row_mask:0xf bank_mask:0xf
	v_fmac_f32_dpp v203, v81, v129 row_shl:1 row_mask:0xf bank_mask:0xf
	v_fmac_f32_dpp v204, v82, v130 row_shl:1 row_mask:0xf bank_mask:0xf
	v_fmac_f32_dpp v205, v83, v131 row_shl:1 row_mask:0xf bank_mask:0xf
	v_fmac_f32_dpp v206, v136, v128 row_shl:1 row_mask:0xf bank_mask:0xf
	v_fmac_f32_dpp v207, v137, v129 row_shl:1 row_mask:0xf bank_mask:0xf
	v_fmac_f32_dpp v208, v138, v130 row_shl:1 row_mask:0xf bank_mask:0xf
	v_fmac_f32_dpp v209, v139, v131 row_shl:1 row_mask:0xf bank_mask:0xf
	v_fmac_f32_dpp v198, v140, v120 row_shl:15 row_mask:0xf bank_mask:0xf
	v_fmac_f32_dpp v199, v141, v121 row_shl:15 row_mask:0xf bank_mask:0xf
	v_fmac_f32_dpp v200, v142, v122 row_shl:15 row_mask:0xf bank_mask:0xf
	v_fmac_f32_dpp v201, v143, v123 row_shl:15 row_mask:0xf bank_mask:0xf
	v_fmac_f32_dpp v202, v84, v120 row_shl:15 row_mask:0xf bank_mask:0xf
	v_fmac_f32_dpp v203, v85, v121 row_shl:15 row_mask:0xf bank_mask:0xf
	v_fmac_f32_dpp v204, v86, v122 row_shl:15 row_mask:0xf bank_mask:0xf
	v_fmac_f32_dpp v205, v87, v123 row_shl:15 row_mask:0xf bank_mask:0xf
	v_fmac_f32_dpp v206, v80, v120 row_shl:15 row_mask:0xf bank_mask:0xf
	v_fmac_f32_dpp v207, v81, v121 row_shl:15 row_mask:0xf bank_mask:0xf
	v_fmac_f32_dpp v208, v82, v122 row_shl:15 row_mask:0xf bank_mask:0xf
	v_fmac_f32_dpp v209, v83, v123 row_shl:15 row_mask:0xf bank_mask:0xf
	v_fmac_f32_dpp v194, v84, v128 row_shr:15 row_mask:0xf bank_mask:0xf
	v_fmac_f32_dpp v195, v85, v129 row_shr:15 row_mask:0xf bank_mask:0xf
	v_fmac_f32_dpp v196, v86, v130 row_shr:15 row_mask:0xf bank_mask:0xf
	v_fmac_f32_dpp v197, v87, v131 row_shr:15 row_mask:0xf bank_mask:0xf
	v_fmac_f32_dpp v198, v80, v128 row_shr:15 row_mask:0xf bank_mask:0xf
	v_fmac_f32_dpp v199, v81, v129 row_shr:15 row_mask:0xf bank_mask:0xf
; #define GAS __attribute__((address_space(1)))
; template <int CTRL> __device__ __forceinline__ float dpp_ror(float v) { return __builtin_bit_cast(float, __builtin_amdgcn_update_dpp(0, __builtin_bit_cast(int, v), CTRL, 0xf, 0xf, false)); }
;     __device__ __forceinline__ void operator()(pg8::f32x4 (&acc)[2][2][4][2], const pg8::Unit& u, int wr_, int wc_, int fr_, int fq_) const {
;     ...
;                 if (e0) { *(GAS pg8::f32x4*)&EG[eb0 + hc] = acc[ai][0][0][n]; *(GAS pg8::f32x4*)&EU[eb0 + hc] = acc[ai][1][0][n]; }
;                 if (e3) { *(GAS pg8::f32x4*)&EG[eb3 + hc] = acc[ai][0][3][n]; *(GAS pg8::f32x4*)&EU[eb3 + hc] = acc[ai][1][3][n]; }
; #pragma unroll
;                 for (int j = 0; j < 4; ++j) {
;                     float pr[4], nx[4], gg[4];
; #pragma unroll
;                     for (int m = 0; m < 4; ++m) { gg[m] = acc[ai][0][m][n][j]; pr[m] = dpp_ror<0x121>(gg[m]); nx[m] = dpp_ror<0x12F>(gg[m]); }
; #pragma unroll
;                     for (int m = 0; m < 4; ++m) {
;                         const float pv = fr > 0 ? pr[m] : (m > 0 ? pr[m > 0 ? m - 1 : 0] : 0.f);
;                         const float nv = fr < 15 ? nx[m] : (m < 3 ? nx[m < 3 ? m + 1 : 3] : 0.f);
;                         const float cv = w0[j] * pv + w1[j] * gg[m] + w2[j] * nv + bb[j];
;                         if (m == 0) { if (e0) EP[eb0 + hc + (unsigned)j] = cv; } if (m == 3) { if (e3) EP[eb3 + hc + (unsigned)j] = cv; }
;                         acc[ai][0][m][n][j] = gelu_tanh(cv) * acc[ai][1][m][n][j];
	v_fmac_f32_dpp v200, v82, v130 row_shr:15 row_mask:0xf bank_mask:0xf
	v_fmac_f32_dpp v201, v83, v131 row_shr:15 row_mask:0xf bank_mask:0xf
	v_fmac_f32_dpp v202, v136, v128 row_shr:15 row_mask:0xf bank_mask:0xf
	v_fmac_f32_dpp v203, v137, v129 row_shr:15 row_mask:0xf bank_mask:0xf
	v_fmac_f32_dpp v204, v138, v130 row_shr:15 row_mask:0xf bank_mask:0xf
	v_fmac_f32_dpp v205, v139, v131 row_shr:15 row_mask:0xf bank_mask:0xf
	v_mov_b32_e32 v235, v232
	s_mov_b64 exec, s[12:13]
	global_store_dwordx4 v235, v[140:143], s[16:17] offset:0
	global_store_dwordx4 v235, v[104:107], s[22:23] offset:0
	global_store_dwordx4 v235, v[194:197], s[20:21] offset:0
	s_mov_b64 exec, s[8:9]
	v_add_u32_e32 v235, 0x5800, v235
	s_mov_b64 exec, s[30:31]
	global_store_dwordx4 v235, v[136:139], s[16:17] offset:0
	global_store_dwordx4 v235, v[64:67], s[22:23] offset:0
	global_store_dwordx4 v235, v[206:209], s[20:21] offset:0
	s_mov_b64 exec, s[8:9]
	v_pk_mul_f32 v[144:145], v[194:195], v[194:195]
	v_pk_mul_f32 v[146:147], v[196:197], v[196:197]
	v_pk_mul_f32 v[148:149], v[198:199], v[198:199]
	v_pk_mul_f32 v[150:151], v[200:201], v[200:201]
	v_pk_mul_f32 v[164:165], v[202:203], v[202:203]
	v_pk_mul_f32 v[166:167], v[204:205], v[204:205]
	v_pk_mul_f32 v[168:169], v[206:207], v[206:207]
	v_pk_mul_f32 v[170:171], v[208:209], v[208:209]
	v_pk_fma_f32 v[144:145], v[144:145], v[174:175], v[172:173]
	v_pk_fma_f32 v[146:147], v[146:147], v[174:175], v[172:173]
	v_pk_fma_f32 v[148:149], v[148:149], v[174:175], v[172:173]
	v_pk_fma_f32 v[150:151], v[150:151], v[174:175], v[172:173]
	v_pk_fma_f32 v[164:165], v[164:165], v[174:175], v[172:173]
	v_pk_fma_f32 v[166:167], v[166:167], v[174:175], v[172:173]
	v_pk_fma_f32 v[168:169], v[168:169], v[174:175], v[172:173]
	v_pk_fma_f32 v[170:171], v[170:171], v[174:175], v[172:173]
	v_pk_mul_f32 v[144:145], v[144:145], v[194:195]
	v_pk_mul_f32 v[146:147], v[146:147], v[196:197]
	v_pk_mul_f32 v[148:149], v[148:149], v[198:199]
	v_pk_mul_f32 v[150:151], v[150:151], v[200:201]
	v_pk_mul_f32 v[164:165], v[164:165], v[202:203]
	v_pk_mul_f32 v[166:167], v[166:167], v[204:205]
	v_pk_mul_f32 v[168:169], v[168:169], v[206:207]
	v_pk_mul_f32 v[170:171], v[170:171], v[208:209]
	v_exp_f32_e32 v144, v144
	v_exp_f32_e32 v146, v146
	v_exp_f32_e32 v148, v148
	v_exp_f32_e32 v150, v150
	v_exp_f32_e32 v164, v164
	v_exp_f32_e32 v166, v166
	v_exp_f32_e32 v168, v168
	v_exp_f32_e32 v170, v170
	v_exp_f32_e32 v145, v145
	v_exp_f32_e32 v147, v147
	v_exp_f32_e32 v149, v149
	v_exp_f32_e32 v151, v151
	v_exp_f32_e32 v165, v165
	v_exp_f32_e32 v167, v167
	v_exp_f32_e32 v169, v169
	v_exp_f32_e32 v171, v171
	v_pk_add_f32 v[144:145], v[144:145], v[210:211]
	v_pk_add_f32 v[146:147], v[146:147], v[210:211]
	v_pk_add_f32 v[148:149], v[148:149], v[210:211]
	v_pk_add_f32 v[150:151], v[150:151], v[210:211]
	v_pk_add_f32 v[164:165], v[164:165], v[210:211]
	v_pk_add_f32 v[166:167], v[166:167], v[210:211]
	v_pk_add_f32 v[168:169], v[168:169], v[210:211]
	v_pk_add_f32 v[170:171], v[170:171], v[210:211]
	v_rcp_f32_e32 v144, v144
	v_rcp_f32_e32 v146, v146
	v_rcp_f32_e32 v148, v148
	v_rcp_f32_e32 v150, v150
	v_rcp_f32_e32 v164, v164
	v_rcp_f32_e32 v166, v166
	v_rcp_f32_e32 v168, v168
	v_rcp_f32_e32 v170, v170
	v_rcp_f32_e32 v145, v145
	v_rcp_f32_e32 v147, v147
	v_rcp_f32_e32 v149, v149
	v_rcp_f32_e32 v151, v151
	v_rcp_f32_e32 v165, v165
	v_rcp_f32_e32 v167, v167
	v_rcp_f32_e32 v169, v169
	v_rcp_f32_e32 v171, v171
	v_pk_mul_f32 v[140:141], v[194:195], v[104:105]
	v_pk_mul_f32 v[142:143], v[196:197], v[106:107]
	v_pk_mul_f32 v[84:85], v[198:199], v[76:77]
	v_pk_mul_f32 v[86:87], v[200:201], v[78:79]
	v_pk_mul_f32 v[80:81], v[202:203], v[72:73]
	v_pk_mul_f32 v[82:83], v[204:205], v[74:75]
	v_pk_mul_f32 v[136:137], v[206:207], v[64:65]
	v_pk_mul_f32 v[138:139], v[208:209], v[66:67]
	v_pk_mul_f32 v[140:141], v[140:141], v[144:145]
	v_pk_mul_f32 v[142:143], v[142:143], v[146:147]
	v_pk_mul_f32 v[84:85], v[84:85], v[148:149]
	v_pk_mul_f32 v[86:87], v[86:87], v[150:151]
	v_pk_mul_f32 v[80:81], v[80:81], v[164:165]
	v_pk_mul_f32 v[82:83], v[82:83], v[166:167]
	v_pk_mul_f32 v[136:137], v[136:137], v[168:169]
	v_pk_mul_f32 v[138:139], v[138:139], v[170:171]
	v_pk_fma_f32 v[194:195], v[182:183], v[116:117], v[190:191]
	v_pk_fma_f32 v[196:197], v[184:185], v[118:119], v[192:193]
	v_pk_fma_f32 v[198:199], v[182:183], v[100:101], v[190:191]
	v_pk_fma_f32 v[200:201], v[184:185], v[102:103], v[192:193]
	v_pk_fma_f32 v[202:203], v[182:183], v[96:97], v[190:191]
	v_pk_fma_f32 v[204:205], v[184:185], v[98:99], v[192:193]
	v_pk_fma_f32 v[206:207], v[182:183], v[112:113], v[190:191]
	v_pk_fma_f32 v[208:209], v[184:185], v[114:115], v[192:193]
	v_fmac_f32_dpp v194, v116, v178 row_shr:1 row_mask:0xf bank_mask:0xf
	v_fmac_f32_dpp v195, v117, v179 row_shr:1 row_mask:0xf bank_mask:0xf
	v_fmac_f32_dpp v196, v118, v180 row_shr:1 row_mask:0xf bank_mask:0xf
	v_fmac_f32_dpp v197, v119, v181 row_shr:1 row_mask:0xf bank_mask:0xf
	v_fmac_f32_dpp v198, v100, v178 row_shr:1 row_mask:0xf bank_mask:0xf
	v_fmac_f32_dpp v199, v101, v179 row_shr:1 row_mask:0xf bank_mask:0xf
	v_fmac_f32_dpp v200, v102, v180 row_shr:1 row_mask:0xf bank_mask:0xf
	v_fmac_f32_dpp v201, v103, v181 row_shr:1 row_mask:0xf bank_mask:0xf
	v_fmac_f32_dpp v202, v96, v178 row_shr:1 row_mask:0xf bank_mask:0xf
	v_fmac_f32_dpp v203, v97, v179 row_shr:1 row_mask:0xf bank_mask:0xf
	v_fmac_f32_dpp v204, v98, v180 row_shr:1 row_mask:0xf bank_mask:0xf
	v_fmac_f32_dpp v205, v99, v181 row_shr:1 row_mask:0xf bank_mask:0xf
	v_fmac_f32_dpp v206, v112, v178 row_shr:1 row_mask:0xf bank_mask:0xf
	v_fmac_f32_dpp v207, v113, v179 row_shr:1 row_mask:0xf bank_mask:0xf
; #define GAS __attribute__((address_space(1)))
; template <int CTRL> __device__ __forceinline__ float dpp_ror(float v) { return __builtin_bit_cast(float, __builtin_amdgcn_update_dpp(0, __builtin_bit_cast(int, v), CTRL, 0xf, 0xf, false)); }
;     __device__ __forceinline__ void operator()(pg8::f32x4 (&acc)[2][2][4][2], const pg8::Unit& u, int wr_, int wc_, int fr_, int fq_) const {
;     ...
;                 if (e0) { *(GAS pg8::f32x4*)&EG[eb0 + hc] = acc[ai][0][0][n]; *(GAS pg8::f32x4*)&EU[eb0 + hc] = acc[ai][1][0][n]; }
;                 if (e3) { *(GAS pg8::f32x4*)&EG[eb3 + hc] = acc[ai][0][3][n]; *(GAS pg8::f32x4*)&EU[eb3 + hc] = acc[ai][1][3][n]; }
; #pragma unroll
;                 for (int j = 0; j < 4; ++j) {
;                     float pr[4], nx[4], gg[4];
; #pragma unroll
;                     for (int m = 0; m < 4; ++m) { gg[m] = acc[ai][0][m][n][j]; pr[m] = dpp_ror<0x121>(gg[m]); nx[m] = dpp_ror<0x12F>(gg[m]); }
; #pragma unroll
;                     for (int m = 0; m < 4; ++m) {
;                         const float pv = fr > 0 ? pr[m] : (m > 0 ? pr[m > 0 ? m - 1 : 0] : 0.f);
;                         const float nv = fr < 15 ? nx[m] : (m < 3 ? nx[m < 3 ? m + 1 : 3] : 0.f);
;                         const float cv = w0[j] * pv + w1[j] * gg[m] + w2[j] * nv + bb[j];
;                         if (m == 0) { if (e0) EP[eb0 + hc + (unsigned)j] = cv; } if (m == 3) { if (e3) EP[eb3 + hc + (unsigned)j] = cv; }
;                         acc[ai][0][m][n][j] = gelu_tanh(cv) * acc[ai][1][m][n][j];
	v_fmac_f32_dpp v208, v114, v180 row_shr:1 row_mask:0xf bank_mask:0xf
	v_fmac_f32_dpp v209, v115, v181 row_shr:1 row_mask:0xf bank_mask:0xf
	v_fmac_f32_dpp v194, v116, v186 row_shl:1 row_mask:0xf bank_mask:0xf
	v_fmac_f32_dpp v195, v117, v187 row_shl:1 row_mask:0xf bank_mask:0xf
	v_fmac_f32_dpp v196, v118, v188 row_shl:1 row_mask:0xf bank_mask:0xf
	v_fmac_f32_dpp v197, v119, v189 row_shl:1 row_mask:0xf bank_mask:0xf
	v_fmac_f32_dpp v198, v100, v186 row_shl:1 row_mask:0xf bank_mask:0xf
	v_fmac_f32_dpp v199, v101, v187 row_shl:1 row_mask:0xf bank_mask:0xf
	v_fmac_f32_dpp v200, v102, v188 row_shl:1 row_mask:0xf bank_mask:0xf
	v_fmac_f32_dpp v201, v103, v189 row_shl:1 row_mask:0xf bank_mask:0xf
	v_fmac_f32_dpp v202, v96, v186 row_shl:1 row_mask:0xf bank_mask:0xf
	v_fmac_f32_dpp v203, v97, v187 row_shl:1 row_mask:0xf bank_mask:0xf
	v_fmac_f32_dpp v204, v98, v188 row_shl:1 row_mask:0xf bank_mask:0xf
	v_fmac_f32_dpp v205, v99, v189 row_shl:1 row_mask:0xf bank_mask:0xf
	v_fmac_f32_dpp v206, v112, v186 row_shl:1 row_mask:0xf bank_mask:0xf
	v_fmac_f32_dpp v207, v113, v187 row_shl:1 row_mask:0xf bank_mask:0xf
	v_fmac_f32_dpp v208, v114, v188 row_shl:1 row_mask:0xf bank_mask:0xf
	v_fmac_f32_dpp v209, v115, v189 row_shl:1 row_mask:0xf bank_mask:0xf
	v_fmac_f32_dpp v198, v116, v178 row_shl:15 row_mask:0xf bank_mask:0xf
	v_fmac_f32_dpp v199, v117, v179 row_shl:15 row_mask:0xf bank_mask:0xf
	v_fmac_f32_dpp v200, v118, v180 row_shl:15 row_mask:0xf bank_mask:0xf
	v_fmac_f32_dpp v201, v119, v181 row_shl:15 row_mask:0xf bank_mask:0xf
	v_fmac_f32_dpp v202, v100, v178 row_shl:15 row_mask:0xf bank_mask:0xf
	v_fmac_f32_dpp v203, v101, v179 row_shl:15 row_mask:0xf bank_mask:0xf
	v_fmac_f32_dpp v204, v102, v180 row_shl:15 row_mask:0xf bank_mask:0xf
	v_fmac_f32_dpp v205, v103, v181 row_shl:15 row_mask:0xf bank_mask:0xf
	v_fmac_f32_dpp v206, v96, v178 row_shl:15 row_mask:0xf bank_mask:0xf
	v_fmac_f32_dpp v207, v97, v179 row_shl:15 row_mask:0xf bank_mask:0xf
	v_fmac_f32_dpp v208, v98, v180 row_shl:15 row_mask:0xf bank_mask:0xf
	v_fmac_f32_dpp v209, v99, v181 row_shl:15 row_mask:0xf bank_mask:0xf
	v_fmac_f32_dpp v194, v100, v186 row_shr:15 row_mask:0xf bank_mask:0xf
	v_fmac_f32_dpp v195, v101, v187 row_shr:15 row_mask:0xf bank_mask:0xf
	v_fmac_f32_dpp v196, v102, v188 row_shr:15 row_mask:0xf bank_mask:0xf
	v_fmac_f32_dpp v197, v103, v189 row_shr:15 row_mask:0xf bank_mask:0xf
	v_fmac_f32_dpp v198, v96, v186 row_shr:15 row_mask:0xf bank_mask:0xf
	v_fmac_f32_dpp v199, v97, v187 row_shr:15 row_mask:0xf bank_mask:0xf
	v_fmac_f32_dpp v200, v98, v188 row_shr:15 row_mask:0xf bank_mask:0xf
	v_fmac_f32_dpp v201, v99, v189 row_shr:15 row_mask:0xf bank_mask:0xf
	v_fmac_f32_dpp v202, v112, v186 row_shr:15 row_mask:0xf bank_mask:0xf
	v_fmac_f32_dpp v203, v113, v187 row_shr:15 row_mask:0xf bank_mask:0xf
	v_fmac_f32_dpp v204, v114, v188 row_shr:15 row_mask:0xf bank_mask:0xf
	v_fmac_f32_dpp v205, v115, v189 row_shr:15 row_mask:0xf bank_mask:0xf
	v_mov_b32_e32 v235, v232
	s_mov_b64 exec, s[12:13]
	global_store_dwordx4 v235, v[116:119], s[16:17] offset:16
	global_store_dwordx4 v235, v[108:111], s[22:23] offset:16
	global_store_dwordx4 v235, v[194:197], s[20:21] offset:16
	s_mov_b64 exec, s[8:9]
	v_add_u32_e32 v235, 0x5800, v235
	s_mov_b64 exec, s[30:31]
	global_store_dwordx4 v235, v[112:115], s[16:17] offset:16
	global_store_dwordx4 v235, v[68:71], s[22:23] offset:16
	global_store_dwordx4 v235, v[206:209], s[20:21] offset:16
	s_mov_b64 exec, s[8:9]
	v_pk_mul_f32 v[144:145], v[194:195], v[194:195]
	v_pk_mul_f32 v[146:147], v[196:197], v[196:197]
	v_pk_mul_f32 v[148:149], v[198:199], v[198:199]
	v_pk_mul_f32 v[150:151], v[200:201], v[200:201]
	v_pk_mul_f32 v[164:165], v[202:203], v[202:203]
	v_pk_mul_f32 v[166:167], v[204:205], v[204:205]
	v_pk_mul_f32 v[168:169], v[206:207], v[206:207]
	v_pk_mul_f32 v[170:171], v[208:209], v[208:209]
	v_pk_fma_f32 v[144:145], v[144:145], v[174:175], v[172:173]
	v_pk_fma_f32 v[146:147], v[146:147], v[174:175], v[172:173]
	v_pk_fma_f32 v[148:149], v[148:149], v[174:175], v[172:173]
	v_pk_fma_f32 v[150:151], v[150:151], v[174:175], v[172:173]
	v_pk_fma_f32 v[164:165], v[164:165], v[174:175], v[172:173]
	v_pk_fma_f32 v[166:167], v[166:167], v[174:175], v[172:173]
	v_pk_fma_f32 v[168:169], v[168:169], v[174:175], v[172:173]
	v_pk_fma_f32 v[170:171], v[170:171], v[174:175], v[172:173]
	v_pk_mul_f32 v[144:145], v[144:145], v[194:195]
	v_pk_mul_f32 v[146:147], v[146:147], v[196:197]
	v_pk_mul_f32 v[148:149], v[148:149], v[198:199]
	v_pk_mul_f32 v[150:151], v[150:151], v[200:201]
	v_pk_mul_f32 v[164:165], v[164:165], v[202:203]
	v_pk_mul_f32 v[166:167], v[166:167], v[204:205]
	v_pk_mul_f32 v[168:169], v[168:169], v[206:207]
	v_pk_mul_f32 v[170:171], v[170:171], v[208:209]
	v_exp_f32_e32 v144, v144
	v_exp_f32_e32 v146, v146
	v_exp_f32_e32 v148, v148
	v_exp_f32_e32 v150, v150
	v_exp_f32_e32 v164, v164
	v_exp_f32_e32 v166, v166
	v_exp_f32_e32 v168, v168
	v_exp_f32_e32 v170, v170
	v_exp_f32_e32 v145, v145
	v_exp_f32_e32 v147, v147
	v_exp_f32_e32 v149, v149
	v_exp_f32_e32 v151, v151
	v_exp_f32_e32 v165, v165
	v_exp_f32_e32 v167, v167
	v_exp_f32_e32 v169, v169
	v_exp_f32_e32 v171, v171
	v_pk_add_f32 v[144:145], v[144:145], v[210:211]
	v_pk_add_f32 v[146:147], v[146:147], v[210:211]
	v_pk_add_f32 v[148:149], v[148:149], v[210:211]
	v_pk_add_f32 v[150:151], v[150:151], v[210:211]
	v_pk_add_f32 v[164:165], v[164:165], v[210:211]
	v_pk_add_f32 v[166:167], v[166:167], v[210:211]
	v_pk_add_f32 v[168:169], v[168:169], v[210:211]
	v_pk_add_f32 v[170:171], v[170:171], v[210:211]
	v_rcp_f32_e32 v144, v144
	v_rcp_f32_e32 v146, v146
	v_rcp_f32_e32 v148, v148
	v_rcp_f32_e32 v150, v150
; __device__ __forceinline__ unsigned cvt_pk_bf16(float lo, float hi) { unsigned r; asm volatile("v_cvt_pk_bf16_f32 %0, %1, %2" : "=v"(r) : "v"(lo), "v"(hi)); return r; }
; #define GAS __attribute__((address_space(1)))
; template <int CTRL> __device__ __forceinline__ float dpp_ror(float v) { return __builtin_bit_cast(float, __builtin_amdgcn_update_dpp(0, __builtin_bit_cast(int, v), CTRL, 0xf, 0xf, false)); }
;     __device__ __forceinline__ void operator()(pg8::f32x4 (&acc)[2][2][4][2], const pg8::Unit& u, int wr_, int wc_, int fr_, int fq_) const {
;     ...
;                 if (e0) { *(GAS pg8::f32x4*)&EG[eb0 + hc] = acc[ai][0][0][n]; *(GAS pg8::f32x4*)&EU[eb0 + hc] = acc[ai][1][0][n]; }
;                 if (e3) { *(GAS pg8::f32x4*)&EG[eb3 + hc] = acc[ai][0][3][n]; *(GAS pg8::f32x4*)&EU[eb3 + hc] = acc[ai][1][3][n]; }
; #pragma unroll
;                 for (int j = 0; j < 4; ++j) {
;                     float pr[4], nx[4], gg[4];
; #pragma unroll
;                     for (int m = 0; m < 4; ++m) { gg[m] = acc[ai][0][m][n][j]; pr[m] = dpp_ror<0x121>(gg[m]); nx[m] = dpp_ror<0x12F>(gg[m]); }
; #pragma unroll
;                     for (int m = 0; m < 4; ++m) {
;                         const float pv = fr > 0 ? pr[m] : (m > 0 ? pr[m > 0 ? m - 1 : 0] : 0.f);
;                         const float nv = fr < 15 ? nx[m] : (m < 3 ? nx[m < 3 ? m + 1 : 3] : 0.f);
;                         const float cv = w0[j] * pv + w1[j] * gg[m] + w2[j] * nv + bb[j];
;                         if (m == 0) { if (e0) EP[eb0 + hc + (unsigned)j] = cv; } if (m == 3) { if (e3) EP[eb3 + hc + (unsigned)j] = cv; }
;                         acc[ai][0][m][n][j] = gelu_tanh(cv) * acc[ai][1][m][n][j];
;                     }
;                 }
;                 asm volatile("" ::: "memory"); __builtin_amdgcn_sched_barrier(0);
;             }
; #pragma unroll
;             for (int m = 0; m < 4; ++m) {
;                 if (!((m == 0 && e0) || (m == 3 && e3))) {
;                     const pg8::f32x4 v0 = acc[ai][0][m][0], v1 = acc[ai][0][m][1];
;                     v4u w; w.x = pg8::cvt_pk_bf16(v0[0], v0[1]); w.y = pg8::cvt_pk_bf16(v0[2], v0[3]); w.z = pg8::cvt_pk_bf16(v1[0], v1[1]); w.w = pg8::cvt_pk_bf16(v1[2], v1[3]);
;                     *(GAS v4u*)&HID[(unsigned)(rbase + m * 16 + fr) * (unsigned)DFF + hc0] = w;
	v_rcp_f32_e32 v164, v164
	v_rcp_f32_e32 v166, v166
	v_rcp_f32_e32 v168, v168
	v_rcp_f32_e32 v170, v170
	v_rcp_f32_e32 v145, v145
	v_rcp_f32_e32 v147, v147
	v_rcp_f32_e32 v149, v149
	v_rcp_f32_e32 v151, v151
	v_rcp_f32_e32 v165, v165
	v_rcp_f32_e32 v167, v167
	v_rcp_f32_e32 v169, v169
	v_rcp_f32_e32 v171, v171
	v_pk_mul_f32 v[116:117], v[194:195], v[108:109]
	v_pk_mul_f32 v[118:119], v[196:197], v[110:111]
	v_pk_mul_f32 v[100:101], v[198:199], v[92:93]
	v_pk_mul_f32 v[102:103], v[200:201], v[94:95]
	v_pk_mul_f32 v[96:97], v[202:203], v[88:89]
	v_pk_mul_f32 v[98:99], v[204:205], v[90:91]
	v_pk_mul_f32 v[112:113], v[206:207], v[68:69]
	v_pk_mul_f32 v[114:115], v[208:209], v[70:71]
	v_pk_mul_f32 v[116:117], v[116:117], v[144:145]
	v_pk_mul_f32 v[118:119], v[118:119], v[146:147]
	v_pk_mul_f32 v[100:101], v[100:101], v[148:149]
	v_pk_mul_f32 v[102:103], v[102:103], v[150:151]
	v_pk_mul_f32 v[96:97], v[96:97], v[164:165]
	v_pk_mul_f32 v[98:99], v[98:99], v[166:167]
	v_pk_mul_f32 v[112:113], v[112:113], v[168:169]
	v_pk_mul_f32 v[114:115], v[114:115], v[170:171]
	v_cvt_pk_bf16_f32 v140, v140, v141
	v_cvt_pk_bf16_f32 v141, v142, v143
	v_cvt_pk_bf16_f32 v142, v116, v117
	v_cvt_pk_bf16_f32 v143, v118, v119
	v_cvt_pk_bf16_f32 v84, v84, v85
	v_cvt_pk_bf16_f32 v85, v86, v87
	v_cvt_pk_bf16_f32 v86, v100, v101
	v_cvt_pk_bf16_f32 v87, v102, v103
	v_cvt_pk_bf16_f32 v80, v80, v81
	v_cvt_pk_bf16_f32 v81, v82, v83
	v_cvt_pk_bf16_f32 v82, v96, v97
	v_cvt_pk_bf16_f32 v83, v98, v99
	v_cvt_pk_bf16_f32 v136, v136, v137
	v_cvt_pk_bf16_f32 v137, v138, v139
	v_cvt_pk_bf16_f32 v138, v112, v113
	v_cvt_pk_bf16_f32 v139, v114, v115
	v_mov_b32_e32 v235, v233
	s_mov_b64 exec, s[10:11]
	global_store_dwordx4 v235, v[140:143], s[18:19]
	s_mov_b64 exec, s[8:9]
	v_add_u32_e32 v235, 0x2c000, v233
	global_store_dwordx4 v235, v[84:87], s[18:19]
	v_add_u32_e32 v235, 0x58000, v233
	global_store_dwordx4 v235, v[80:83], s[18:19]
	v_add_u32_e32 v235, 0x84000, v233
	s_mov_b64 exec, s[62:63]
	global_store_dwordx4 v235, v[136:139], s[18:19]
	s_mov_b64 exec, s[8:9]
	v_pk_fma_f32 v[194:195], v[124:125], v[60:61], v[132:133]
	v_pk_fma_f32 v[196:197], v[126:127], v[62:63], v[134:135]
	v_pk_fma_f32 v[198:199], v[124:125], v[20:21], v[132:133]
	v_pk_fma_f32 v[200:201], v[126:127], v[22:23], v[134:135]
	v_pk_fma_f32 v[202:203], v[124:125], v[16:17], v[132:133]
	v_pk_fma_f32 v[204:205], v[126:127], v[18:19], v[134:135]
	v_pk_fma_f32 v[206:207], v[124:125], v[56:57], v[132:133]
	v_pk_fma_f32 v[208:209], v[126:127], v[58:59], v[134:135]
	v_fmac_f32_dpp v194, v60, v120 row_shr:1 row_mask:0xf bank_mask:0xf
	v_fmac_f32_dpp v195, v61, v121 row_shr:1 row_mask:0xf bank_mask:0xf
	v_fmac_f32_dpp v196, v62, v122 row_shr:1 row_mask:0xf bank_mask:0xf
	v_fmac_f32_dpp v197, v63, v123 row_shr:1 row_mask:0xf bank_mask:0xf
	v_fmac_f32_dpp v198, v20, v120 row_shr:1 row_mask:0xf bank_mask:0xf
	v_fmac_f32_dpp v199, v21, v121 row_shr:1 row_mask:0xf bank_mask:0xf
	v_fmac_f32_dpp v200, v22, v122 row_shr:1 row_mask:0xf bank_mask:0xf
	v_fmac_f32_dpp v201, v23, v123 row_shr:1 row_mask:0xf bank_mask:0xf
	v_fmac_f32_dpp v202, v16, v120 row_shr:1 row_mask:0xf bank_mask:0xf
	v_fmac_f32_dpp v203, v17, v121 row_shr:1 row_mask:0xf bank_mask:0xf
	v_fmac_f32_dpp v204, v18, v122 row_shr:1 row_mask:0xf bank_mask:0xf
	v_fmac_f32_dpp v205, v19, v123 row_shr:1 row_mask:0xf bank_mask:0xf
	v_fmac_f32_dpp v206, v56, v120 row_shr:1 row_mask:0xf bank_mask:0xf
	v_fmac_f32_dpp v207, v57, v121 row_shr:1 row_mask:0xf bank_mask:0xf
	v_fmac_f32_dpp v208, v58, v122 row_shr:1 row_mask:0xf bank_mask:0xf
	v_fmac_f32_dpp v209, v59, v123 row_shr:1 row_mask:0xf bank_mask:0xf
	v_fmac_f32_dpp v194, v60, v128 row_shl:1 row_mask:0xf bank_mask:0xf
	v_fmac_f32_dpp v195, v61, v129 row_shl:1 row_mask:0xf bank_mask:0xf
	v_fmac_f32_dpp v196, v62, v130 row_shl:1 row_mask:0xf bank_mask:0xf
	v_fmac_f32_dpp v197, v63, v131 row_shl:1 row_mask:0xf bank_mask:0xf
	v_fmac_f32_dpp v198, v20, v128 row_shl:1 row_mask:0xf bank_mask:0xf
	v_fmac_f32_dpp v199, v21, v129 row_shl:1 row_mask:0xf bank_mask:0xf
	v_fmac_f32_dpp v200, v22, v130 row_shl:1 row_mask:0xf bank_mask:0xf
	v_fmac_f32_dpp v201, v23, v131 row_shl:1 row_mask:0xf bank_mask:0xf
	v_fmac_f32_dpp v202, v16, v128 row_shl:1 row_mask:0xf bank_mask:0xf
	v_fmac_f32_dpp v203, v17, v129 row_shl:1 row_mask:0xf bank_mask:0xf
	v_fmac_f32_dpp v204, v18, v130 row_shl:1 row_mask:0xf bank_mask:0xf
	v_fmac_f32_dpp v205, v19, v131 row_shl:1 row_mask:0xf bank_mask:0xf
	v_fmac_f32_dpp v206, v56, v128 row_shl:1 row_mask:0xf bank_mask:0xf
	v_fmac_f32_dpp v207, v57, v129 row_shl:1 row_mask:0xf bank_mask:0xf
	v_fmac_f32_dpp v208, v58, v130 row_shl:1 row_mask:0xf bank_mask:0xf
	v_fmac_f32_dpp v209, v59, v131 row_shl:1 row_mask:0xf bank_mask:0xf
	v_fmac_f32_dpp v198, v60, v120 row_shl:15 row_mask:0xf bank_mask:0xf
	v_fmac_f32_dpp v199, v61, v121 row_shl:15 row_mask:0xf bank_mask:0xf
	v_fmac_f32_dpp v200, v62, v122 row_shl:15 row_mask:0xf bank_mask:0xf
	v_fmac_f32_dpp v201, v63, v123 row_shl:15 row_mask:0xf bank_mask:0xf
	v_fmac_f32_dpp v202, v20, v120 row_shl:15 row_mask:0xf bank_mask:0xf
	v_fmac_f32_dpp v203, v21, v121 row_shl:15 row_mask:0xf bank_mask:0xf
	v_fmac_f32_dpp v204, v22, v122 row_shl:15 row_mask:0xf bank_mask:0xf
	v_fmac_f32_dpp v205, v23, v123 row_shl:15 row_mask:0xf bank_mask:0xf
	v_fmac_f32_dpp v206, v16, v120 row_shl:15 row_mask:0xf bank_mask:0xf
	v_fmac_f32_dpp v207, v17, v121 row_shl:15 row_mask:0xf bank_mask:0xf
	v_fmac_f32_dpp v208, v18, v122 row_shl:15 row_mask:0xf bank_mask:0xf
	v_fmac_f32_dpp v209, v19, v123 row_shl:15 row_mask:0xf bank_mask:0xf
	v_fmac_f32_dpp v194, v20, v128 row_shr:15 row_mask:0xf bank_mask:0xf
; #define GAS __attribute__((address_space(1)))
; template <int CTRL> __device__ __forceinline__ float dpp_ror(float v) { return __builtin_bit_cast(float, __builtin_amdgcn_update_dpp(0, __builtin_bit_cast(int, v), CTRL, 0xf, 0xf, false)); }
;     __device__ __forceinline__ void operator()(pg8::f32x4 (&acc)[2][2][4][2], const pg8::Unit& u, int wr_, int wc_, int fr_, int fq_) const {
;     ...
;                 if (e0) { *(GAS pg8::f32x4*)&EG[eb0 + hc] = acc[ai][0][0][n]; *(GAS pg8::f32x4*)&EU[eb0 + hc] = acc[ai][1][0][n]; }
;                 if (e3) { *(GAS pg8::f32x4*)&EG[eb3 + hc] = acc[ai][0][3][n]; *(GAS pg8::f32x4*)&EU[eb3 + hc] = acc[ai][1][3][n]; }
; #pragma unroll
;                 for (int j = 0; j < 4; ++j) {
;                     float pr[4], nx[4], gg[4];
; #pragma unroll
;                     for (int m = 0; m < 4; ++m) { gg[m] = acc[ai][0][m][n][j]; pr[m] = dpp_ror<0x121>(gg[m]); nx[m] = dpp_ror<0x12F>(gg[m]); }
; #pragma unroll
;                     for (int m = 0; m < 4; ++m) {
;                         const float pv = fr > 0 ? pr[m] : (m > 0 ? pr[m > 0 ? m - 1 : 0] : 0.f);
;                         const float nv = fr < 15 ? nx[m] : (m < 3 ? nx[m < 3 ? m + 1 : 3] : 0.f);
;                         const float cv = w0[j] * pv + w1[j] * gg[m] + w2[j] * nv + bb[j];
;                         if (m == 0) { if (e0) EP[eb0 + hc + (unsigned)j] = cv; } if (m == 3) { if (e3) EP[eb3 + hc + (unsigned)j] = cv; }
;                         acc[ai][0][m][n][j] = gelu_tanh(cv) * acc[ai][1][m][n][j];
	v_fmac_f32_dpp v195, v21, v129 row_shr:15 row_mask:0xf bank_mask:0xf
	v_fmac_f32_dpp v196, v22, v130 row_shr:15 row_mask:0xf bank_mask:0xf
	v_fmac_f32_dpp v197, v23, v131 row_shr:15 row_mask:0xf bank_mask:0xf
	v_fmac_f32_dpp v198, v16, v128 row_shr:15 row_mask:0xf bank_mask:0xf
	v_fmac_f32_dpp v199, v17, v129 row_shr:15 row_mask:0xf bank_mask:0xf
	v_fmac_f32_dpp v200, v18, v130 row_shr:15 row_mask:0xf bank_mask:0xf
	v_fmac_f32_dpp v201, v19, v131 row_shr:15 row_mask:0xf bank_mask:0xf
	v_fmac_f32_dpp v202, v56, v128 row_shr:15 row_mask:0xf bank_mask:0xf
	v_fmac_f32_dpp v203, v57, v129 row_shr:15 row_mask:0xf bank_mask:0xf
	v_fmac_f32_dpp v204, v58, v130 row_shr:15 row_mask:0xf bank_mask:0xf
	v_fmac_f32_dpp v205, v59, v131 row_shr:15 row_mask:0xf bank_mask:0xf
	v_add_u32_e32 v235, 0x16000, v232
	s_mov_b64 exec, s[12:13]
	global_store_dwordx4 v235, v[60:63], s[16:17] offset:0
	global_store_dwordx4 v235, v[40:43], s[22:23] offset:0
	global_store_dwordx4 v235, v[194:197], s[20:21] offset:0
	s_mov_b64 exec, s[8:9]
	v_add_u32_e32 v235, 0x5800, v235
	s_mov_b64 exec, s[30:31]
	global_store_dwordx4 v235, v[56:59], s[16:17] offset:0
	global_store_dwordx4 v235, v[0:3], s[22:23] offset:0
	global_store_dwordx4 v235, v[206:209], s[20:21] offset:0
	s_mov_b64 exec, s[8:9]
	v_pk_mul_f32 v[144:145], v[194:195], v[194:195]
	v_pk_mul_f32 v[146:147], v[196:197], v[196:197]
	v_pk_mul_f32 v[148:149], v[198:199], v[198:199]
	v_pk_mul_f32 v[150:151], v[200:201], v[200:201]
	v_pk_mul_f32 v[164:165], v[202:203], v[202:203]
	v_pk_mul_f32 v[166:167], v[204:205], v[204:205]
	v_pk_mul_f32 v[168:169], v[206:207], v[206:207]
	v_pk_mul_f32 v[170:171], v[208:209], v[208:209]
	v_pk_fma_f32 v[144:145], v[144:145], v[174:175], v[172:173]
	v_pk_fma_f32 v[146:147], v[146:147], v[174:175], v[172:173]
	v_pk_fma_f32 v[148:149], v[148:149], v[174:175], v[172:173]
	v_pk_fma_f32 v[150:151], v[150:151], v[174:175], v[172:173]
	v_pk_fma_f32 v[164:165], v[164:165], v[174:175], v[172:173]
	v_pk_fma_f32 v[166:167], v[166:167], v[174:175], v[172:173]
	v_pk_fma_f32 v[168:169], v[168:169], v[174:175], v[172:173]
	v_pk_fma_f32 v[170:171], v[170:171], v[174:175], v[172:173]
	v_pk_mul_f32 v[144:145], v[144:145], v[194:195]
	v_pk_mul_f32 v[146:147], v[146:147], v[196:197]
	v_pk_mul_f32 v[148:149], v[148:149], v[198:199]
	v_pk_mul_f32 v[150:151], v[150:151], v[200:201]
	v_pk_mul_f32 v[164:165], v[164:165], v[202:203]
	v_pk_mul_f32 v[166:167], v[166:167], v[204:205]
	v_pk_mul_f32 v[168:169], v[168:169], v[206:207]
	v_pk_mul_f32 v[170:171], v[170:171], v[208:209]
	v_exp_f32_e32 v144, v144
	v_exp_f32_e32 v146, v146
	v_exp_f32_e32 v148, v148
	v_exp_f32_e32 v150, v150
	v_exp_f32_e32 v164, v164
	v_exp_f32_e32 v166, v166
	v_exp_f32_e32 v168, v168
	v_exp_f32_e32 v170, v170
	v_exp_f32_e32 v145, v145
	v_exp_f32_e32 v147, v147
	v_exp_f32_e32 v149, v149
	v_exp_f32_e32 v151, v151
	v_exp_f32_e32 v165, v165
	v_exp_f32_e32 v167, v167
	v_exp_f32_e32 v169, v169
	v_exp_f32_e32 v171, v171
	v_pk_add_f32 v[144:145], v[144:145], v[210:211]
	v_pk_add_f32 v[146:147], v[146:147], v[210:211]
	v_pk_add_f32 v[148:149], v[148:149], v[210:211]
	v_pk_add_f32 v[150:151], v[150:151], v[210:211]
	v_pk_add_f32 v[164:165], v[164:165], v[210:211]
	v_pk_add_f32 v[166:167], v[166:167], v[210:211]
	v_pk_add_f32 v[168:169], v[168:169], v[210:211]
	v_pk_add_f32 v[170:171], v[170:171], v[210:211]
	v_rcp_f32_e32 v144, v144
	v_rcp_f32_e32 v146, v146
	v_rcp_f32_e32 v148, v148
	v_rcp_f32_e32 v150, v150
	v_rcp_f32_e32 v164, v164
	v_rcp_f32_e32 v166, v166
	v_rcp_f32_e32 v168, v168
	v_rcp_f32_e32 v170, v170
	v_rcp_f32_e32 v145, v145
	v_rcp_f32_e32 v147, v147
	v_rcp_f32_e32 v149, v149
	v_rcp_f32_e32 v151, v151
	v_rcp_f32_e32 v165, v165
	v_rcp_f32_e32 v167, v167
	v_rcp_f32_e32 v169, v169
	v_rcp_f32_e32 v171, v171
	v_pk_mul_f32 v[60:61], v[194:195], v[40:41]
	v_pk_mul_f32 v[62:63], v[196:197], v[42:43]
	v_pk_mul_f32 v[20:21], v[198:199], v[12:13]
	v_pk_mul_f32 v[22:23], v[200:201], v[14:15]
	v_pk_mul_f32 v[16:17], v[202:203], v[8:9]
	v_pk_mul_f32 v[18:19], v[204:205], v[10:11]
	v_pk_mul_f32 v[56:57], v[206:207], v[0:1]
	v_pk_mul_f32 v[58:59], v[208:209], v[2:3]
	v_pk_mul_f32 v[60:61], v[60:61], v[144:145]
	v_pk_mul_f32 v[62:63], v[62:63], v[146:147]
	v_pk_mul_f32 v[20:21], v[20:21], v[148:149]
	v_pk_mul_f32 v[22:23], v[22:23], v[150:151]
	v_pk_mul_f32 v[16:17], v[16:17], v[164:165]
	v_pk_mul_f32 v[18:19], v[18:19], v[166:167]
	v_pk_mul_f32 v[56:57], v[56:57], v[168:169]
	v_pk_mul_f32 v[58:59], v[58:59], v[170:171]
	v_pk_fma_f32 v[194:195], v[182:183], v[52:53], v[190:191]
	v_pk_fma_f32 v[196:197], v[184:185], v[54:55], v[192:193]
	v_pk_fma_f32 v[198:199], v[182:183], v[36:37], v[190:191]
	v_pk_fma_f32 v[200:201], v[184:185], v[38:39], v[192:193]
	v_pk_fma_f32 v[202:203], v[182:183], v[32:33], v[190:191]
	v_pk_fma_f32 v[204:205], v[184:185], v[34:35], v[192:193]
	v_pk_fma_f32 v[206:207], v[182:183], v[48:49], v[190:191]
	v_pk_fma_f32 v[208:209], v[184:185], v[50:51], v[192:193]
	v_fmac_f32_dpp v194, v52, v178 row_shr:1 row_mask:0xf bank_mask:0xf
	v_fmac_f32_dpp v195, v53, v179 row_shr:1 row_mask:0xf bank_mask:0xf
	v_fmac_f32_dpp v196, v54, v180 row_shr:1 row_mask:0xf bank_mask:0xf
	v_fmac_f32_dpp v197, v55, v181 row_shr:1 row_mask:0xf bank_mask:0xf
	v_fmac_f32_dpp v198, v36, v178 row_shr:1 row_mask:0xf bank_mask:0xf
	v_fmac_f32_dpp v199, v37, v179 row_shr:1 row_mask:0xf bank_mask:0xf
	v_fmac_f32_dpp v200, v38, v180 row_shr:1 row_mask:0xf bank_mask:0xf
	v_fmac_f32_dpp v201, v39, v181 row_shr:1 row_mask:0xf bank_mask:0xf
	v_fmac_f32_dpp v202, v32, v178 row_shr:1 row_mask:0xf bank_mask:0xf
	v_fmac_f32_dpp v203, v33, v179 row_shr:1 row_mask:0xf bank_mask:0xf
; #define GAS __attribute__((address_space(1)))
; template <int CTRL> __device__ __forceinline__ float dpp_ror(float v) { return __builtin_bit_cast(float, __builtin_amdgcn_update_dpp(0, __builtin_bit_cast(int, v), CTRL, 0xf, 0xf, false)); }
;     __device__ __forceinline__ void operator()(pg8::f32x4 (&acc)[2][2][4][2], const pg8::Unit& u, int wr_, int wc_, int fr_, int fq_) const {
;     ...
;                 if (e0) { *(GAS pg8::f32x4*)&EG[eb0 + hc] = acc[ai][0][0][n]; *(GAS pg8::f32x4*)&EU[eb0 + hc] = acc[ai][1][0][n]; }
;                 if (e3) { *(GAS pg8::f32x4*)&EG[eb3 + hc] = acc[ai][0][3][n]; *(GAS pg8::f32x4*)&EU[eb3 + hc] = acc[ai][1][3][n]; }
; #pragma unroll
;                 for (int j = 0; j < 4; ++j) {
;                     float pr[4], nx[4], gg[4];
; #pragma unroll
;                     for (int m = 0; m < 4; ++m) { gg[m] = acc[ai][0][m][n][j]; pr[m] = dpp_ror<0x121>(gg[m]); nx[m] = dpp_ror<0x12F>(gg[m]); }
; #pragma unroll
;                     for (int m = 0; m < 4; ++m) {
;                         const float pv = fr > 0 ? pr[m] : (m > 0 ? pr[m > 0 ? m - 1 : 0] : 0.f);
;                         const float nv = fr < 15 ? nx[m] : (m < 3 ? nx[m < 3 ? m + 1 : 3] : 0.f);
;                         const float cv = w0[j] * pv + w1[j] * gg[m] + w2[j] * nv + bb[j];
;                         if (m == 0) { if (e0) EP[eb0 + hc + (unsigned)j] = cv; } if (m == 3) { if (e3) EP[eb3 + hc + (unsigned)j] = cv; }
;                         acc[ai][0][m][n][j] = gelu_tanh(cv) * acc[ai][1][m][n][j];
	v_fmac_f32_dpp v204, v34, v180 row_shr:1 row_mask:0xf bank_mask:0xf
	v_fmac_f32_dpp v205, v35, v181 row_shr:1 row_mask:0xf bank_mask:0xf
	v_fmac_f32_dpp v206, v48, v178 row_shr:1 row_mask:0xf bank_mask:0xf
	v_fmac_f32_dpp v207, v49, v179 row_shr:1 row_mask:0xf bank_mask:0xf
	v_fmac_f32_dpp v208, v50, v180 row_shr:1 row_mask:0xf bank_mask:0xf
	v_fmac_f32_dpp v209, v51, v181 row_shr:1 row_mask:0xf bank_mask:0xf
	v_fmac_f32_dpp v194, v52, v186 row_shl:1 row_mask:0xf bank_mask:0xf
	v_fmac_f32_dpp v195, v53, v187 row_shl:1 row_mask:0xf bank_mask:0xf
	v_fmac_f32_dpp v196, v54, v188 row_shl:1 row_mask:0xf bank_mask:0xf
	v_fmac_f32_dpp v197, v55, v189 row_shl:1 row_mask:0xf bank_mask:0xf
	v_fmac_f32_dpp v198, v36, v186 row_shl:1 row_mask:0xf bank_mask:0xf
	v_fmac_f32_dpp v199, v37, v187 row_shl:1 row_mask:0xf bank_mask:0xf
	v_fmac_f32_dpp v200, v38, v188 row_shl:1 row_mask:0xf bank_mask:0xf
	v_fmac_f32_dpp v201, v39, v189 row_shl:1 row_mask:0xf bank_mask:0xf
	v_fmac_f32_dpp v202, v32, v186 row_shl:1 row_mask:0xf bank_mask:0xf
	v_fmac_f32_dpp v203, v33, v187 row_shl:1 row_mask:0xf bank_mask:0xf
	v_fmac_f32_dpp v204, v34, v188 row_shl:1 row_mask:0xf bank_mask:0xf
	v_fmac_f32_dpp v205, v35, v189 row_shl:1 row_mask:0xf bank_mask:0xf
	v_fmac_f32_dpp v206, v48, v186 row_shl:1 row_mask:0xf bank_mask:0xf
	v_fmac_f32_dpp v207, v49, v187 row_shl:1 row_mask:0xf bank_mask:0xf
	v_fmac_f32_dpp v208, v50, v188 row_shl:1 row_mask:0xf bank_mask:0xf
	v_fmac_f32_dpp v209, v51, v189 row_shl:1 row_mask:0xf bank_mask:0xf
	v_fmac_f32_dpp v198, v52, v178 row_shl:15 row_mask:0xf bank_mask:0xf
	v_fmac_f32_dpp v199, v53, v179 row_shl:15 row_mask:0xf bank_mask:0xf
	v_fmac_f32_dpp v200, v54, v180 row_shl:15 row_mask:0xf bank_mask:0xf
	v_fmac_f32_dpp v201, v55, v181 row_shl:15 row_mask:0xf bank_mask:0xf
	v_fmac_f32_dpp v202, v36, v178 row_shl:15 row_mask:0xf bank_mask:0xf
	v_fmac_f32_dpp v203, v37, v179 row_shl:15 row_mask:0xf bank_mask:0xf
	v_fmac_f32_dpp v204, v38, v180 row_shl:15 row_mask:0xf bank_mask:0xf
	v_fmac_f32_dpp v205, v39, v181 row_shl:15 row_mask:0xf bank_mask:0xf
	v_fmac_f32_dpp v206, v32, v178 row_shl:15 row_mask:0xf bank_mask:0xf
	v_fmac_f32_dpp v207, v33, v179 row_shl:15 row_mask:0xf bank_mask:0xf
	v_fmac_f32_dpp v208, v34, v180 row_shl:15 row_mask:0xf bank_mask:0xf
	v_fmac_f32_dpp v209, v35, v181 row_shl:15 row_mask:0xf bank_mask:0xf
	v_fmac_f32_dpp v194, v36, v186 row_shr:15 row_mask:0xf bank_mask:0xf
	v_fmac_f32_dpp v195, v37, v187 row_shr:15 row_mask:0xf bank_mask:0xf
	v_fmac_f32_dpp v196, v38, v188 row_shr:15 row_mask:0xf bank_mask:0xf
	v_fmac_f32_dpp v197, v39, v189 row_shr:15 row_mask:0xf bank_mask:0xf
	v_fmac_f32_dpp v198, v32, v186 row_shr:15 row_mask:0xf bank_mask:0xf
	v_fmac_f32_dpp v199, v33, v187 row_shr:15 row_mask:0xf bank_mask:0xf
	v_fmac_f32_dpp v200, v34, v188 row_shr:15 row_mask:0xf bank_mask:0xf
	v_fmac_f32_dpp v201, v35, v189 row_shr:15 row_mask:0xf bank_mask:0xf
	v_fmac_f32_dpp v202, v48, v186 row_shr:15 row_mask:0xf bank_mask:0xf
	v_fmac_f32_dpp v203, v49, v187 row_shr:15 row_mask:0xf bank_mask:0xf
	v_fmac_f32_dpp v204, v50, v188 row_shr:15 row_mask:0xf bank_mask:0xf
	v_fmac_f32_dpp v205, v51, v189 row_shr:15 row_mask:0xf bank_mask:0xf
	v_add_u32_e32 v235, 0x16000, v232
	s_mov_b64 exec, s[12:13]
	global_store_dwordx4 v235, v[52:55], s[16:17] offset:16
	global_store_dwordx4 v235, v[44:47], s[22:23] offset:16
	global_store_dwordx4 v235, v[194:197], s[20:21] offset:16
	s_mov_b64 exec, s[8:9]
	v_add_u32_e32 v235, 0x5800, v235
	s_mov_b64 exec, s[30:31]
	global_store_dwordx4 v235, v[48:51], s[16:17] offset:16
	global_store_dwordx4 v235, v[4:7], s[22:23] offset:16
	global_store_dwordx4 v235, v[206:209], s[20:21] offset:16
	s_mov_b64 exec, s[8:9]
	v_pk_mul_f32 v[144:145], v[194:195], v[194:195]
	v_pk_mul_f32 v[146:147], v[196:197], v[196:197]
	v_pk_mul_f32 v[148:149], v[198:199], v[198:199]
	v_pk_mul_f32 v[150:151], v[200:201], v[200:201]
	v_pk_mul_f32 v[164:165], v[202:203], v[202:203]
; __device__ __forceinline__ unsigned cvt_pk_bf16(float lo, float hi) { unsigned r; asm volatile("v_cvt_pk_bf16_f32 %0, %1, %2" : "=v"(r) : "v"(lo), "v"(hi)); return r; }
; #define GAS __attribute__((address_space(1)))
; template <int CTRL> __device__ __forceinline__ float dpp_ror(float v) { return __builtin_bit_cast(float, __builtin_amdgcn_update_dpp(0, __builtin_bit_cast(int, v), CTRL, 0xf, 0xf, false)); }
; __device__ __forceinline__ float gelu_tanh(float x) {
;     const float t = x * (1.0f + 0.044715f * x * x) * (-2.302208198f);
;     const float e = __builtin_amdgcn_exp2f(t);
;     return x * __builtin_amdgcn_rcpf(1.0f + e);
; }
;     __device__ __forceinline__ void operator()(pg8::f32x4 (&acc)[2][2][4][2], const pg8::Unit& u, int wr_, int wc_, int fr_, int fq_) const {
;     ...
;                 for (int j = 0; j < 4; ++j) {
;                     float pr[4], nx[4], gg[4];
; #pragma unroll
;                     for (int m = 0; m < 4; ++m) { gg[m] = acc[ai][0][m][n][j]; pr[m] = dpp_ror<0x121>(gg[m]); nx[m] = dpp_ror<0x12F>(gg[m]); }
; #pragma unroll
;                     for (int m = 0; m < 4; ++m) {
;                         const float pv = fr > 0 ? pr[m] : (m > 0 ? pr[m > 0 ? m - 1 : 0] : 0.f);
;                         const float nv = fr < 15 ? nx[m] : (m < 3 ? nx[m < 3 ? m + 1 : 3] : 0.f);
;                         const float cv = w0[j] * pv + w1[j] * gg[m] + w2[j] * nv + bb[j];
;                         if (m == 0) { if (e0) EP[eb0 + hc + (unsigned)j] = cv; } if (m == 3) { if (e3) EP[eb3 + hc + (unsigned)j] = cv; }
;                         acc[ai][0][m][n][j] = gelu_tanh(cv) * acc[ai][1][m][n][j];
;                     }
;                 }
;                 asm volatile("" ::: "memory"); __builtin_amdgcn_sched_barrier(0);
;             }
; #pragma unroll
;             for (int m = 0; m < 4; ++m) {
;                 if (!((m == 0 && e0) || (m == 3 && e3))) {
;                     const pg8::f32x4 v0 = acc[ai][0][m][0], v1 = acc[ai][0][m][1];
;                     v4u w; w.x = pg8::cvt_pk_bf16(v0[0], v0[1]); w.y = pg8::cvt_pk_bf16(v0[2], v0[3]); w.z = pg8::cvt_pk_bf16(v1[0], v1[1]); w.w = pg8::cvt_pk_bf16(v1[2], v1[3]);
;                     *(GAS v4u*)&HID[(unsigned)(rbase + m * 16 + fr) * (unsigned)DFF + hc0] = w;
;                 }
	v_pk_mul_f32 v[166:167], v[204:205], v[204:205]
	v_pk_mul_f32 v[168:169], v[206:207], v[206:207]
	v_pk_mul_f32 v[170:171], v[208:209], v[208:209]
	v_pk_fma_f32 v[144:145], v[144:145], v[174:175], v[172:173]
	v_pk_fma_f32 v[146:147], v[146:147], v[174:175], v[172:173]
	v_pk_fma_f32 v[148:149], v[148:149], v[174:175], v[172:173]
	v_pk_fma_f32 v[150:151], v[150:151], v[174:175], v[172:173]
	v_pk_fma_f32 v[164:165], v[164:165], v[174:175], v[172:173]
	v_pk_fma_f32 v[166:167], v[166:167], v[174:175], v[172:173]
	v_pk_fma_f32 v[168:169], v[168:169], v[174:175], v[172:173]
	v_pk_fma_f32 v[170:171], v[170:171], v[174:175], v[172:173]
	v_pk_mul_f32 v[144:145], v[144:145], v[194:195]
	v_pk_mul_f32 v[146:147], v[146:147], v[196:197]
	v_pk_mul_f32 v[148:149], v[148:149], v[198:199]
	v_pk_mul_f32 v[150:151], v[150:151], v[200:201]
	v_pk_mul_f32 v[164:165], v[164:165], v[202:203]
	v_pk_mul_f32 v[166:167], v[166:167], v[204:205]
	v_pk_mul_f32 v[168:169], v[168:169], v[206:207]
	v_pk_mul_f32 v[170:171], v[170:171], v[208:209]
	v_exp_f32_e32 v144, v144
	v_exp_f32_e32 v146, v146
	v_exp_f32_e32 v148, v148
	v_exp_f32_e32 v150, v150
	v_exp_f32_e32 v164, v164
	v_exp_f32_e32 v166, v166
	v_exp_f32_e32 v168, v168
	v_exp_f32_e32 v170, v170
	v_exp_f32_e32 v145, v145
	v_exp_f32_e32 v147, v147
	v_exp_f32_e32 v149, v149
	v_exp_f32_e32 v151, v151
	v_exp_f32_e32 v165, v165
	v_exp_f32_e32 v167, v167
	v_exp_f32_e32 v169, v169
	v_exp_f32_e32 v171, v171
	v_pk_add_f32 v[144:145], v[144:145], v[210:211]
	v_pk_add_f32 v[146:147], v[146:147], v[210:211]
	v_pk_add_f32 v[148:149], v[148:149], v[210:211]
	v_pk_add_f32 v[150:151], v[150:151], v[210:211]
	v_pk_add_f32 v[164:165], v[164:165], v[210:211]
	v_pk_add_f32 v[166:167], v[166:167], v[210:211]
	v_pk_add_f32 v[168:169], v[168:169], v[210:211]
	v_pk_add_f32 v[170:171], v[170:171], v[210:211]
	v_rcp_f32_e32 v144, v144
	v_rcp_f32_e32 v146, v146
	v_rcp_f32_e32 v148, v148
	v_rcp_f32_e32 v150, v150
	v_rcp_f32_e32 v164, v164
	v_rcp_f32_e32 v166, v166
	v_rcp_f32_e32 v168, v168
	v_rcp_f32_e32 v170, v170
	v_rcp_f32_e32 v145, v145
	v_rcp_f32_e32 v147, v147
	v_rcp_f32_e32 v149, v149
	v_rcp_f32_e32 v151, v151
	v_rcp_f32_e32 v165, v165
	v_rcp_f32_e32 v167, v167
	v_rcp_f32_e32 v169, v169
	v_rcp_f32_e32 v171, v171
	v_pk_mul_f32 v[52:53], v[194:195], v[44:45]
	v_pk_mul_f32 v[54:55], v[196:197], v[46:47]
	v_pk_mul_f32 v[36:37], v[198:199], v[28:29]
	v_pk_mul_f32 v[38:39], v[200:201], v[30:31]
	v_pk_mul_f32 v[32:33], v[202:203], v[24:25]
	v_pk_mul_f32 v[34:35], v[204:205], v[26:27]
	v_pk_mul_f32 v[48:49], v[206:207], v[4:5]
	v_pk_mul_f32 v[50:51], v[208:209], v[6:7]
	v_pk_mul_f32 v[52:53], v[52:53], v[144:145]
	v_pk_mul_f32 v[54:55], v[54:55], v[146:147]
	v_pk_mul_f32 v[36:37], v[36:37], v[148:149]
	v_pk_mul_f32 v[38:39], v[38:39], v[150:151]
	v_pk_mul_f32 v[32:33], v[32:33], v[164:165]
	v_pk_mul_f32 v[34:35], v[34:35], v[166:167]
	v_pk_mul_f32 v[48:49], v[48:49], v[168:169]
	v_pk_mul_f32 v[50:51], v[50:51], v[170:171]
	v_cvt_pk_bf16_f32 v60, v60, v61
	v_cvt_pk_bf16_f32 v61, v62, v63
	v_cvt_pk_bf16_f32 v62, v52, v53
	v_cvt_pk_bf16_f32 v63, v54, v55
	v_cvt_pk_bf16_f32 v20, v20, v21
	v_cvt_pk_bf16_f32 v21, v22, v23
	v_cvt_pk_bf16_f32 v22, v36, v37
	v_cvt_pk_bf16_f32 v23, v38, v39
	v_cvt_pk_bf16_f32 v16, v16, v17
	v_cvt_pk_bf16_f32 v17, v18, v19
	v_cvt_pk_bf16_f32 v18, v32, v33
	v_cvt_pk_bf16_f32 v19, v34, v35
	v_cvt_pk_bf16_f32 v56, v56, v57
	v_cvt_pk_bf16_f32 v57, v58, v59
	v_cvt_pk_bf16_f32 v58, v48, v49
	v_cvt_pk_bf16_f32 v59, v50, v51
	v_add_u32_e32 v235, 0x160000, v233
	s_mov_b64 exec, s[10:11]
	global_store_dwordx4 v235, v[60:63], s[18:19]
	s_mov_b64 exec, s[8:9]
	v_add_u32_e32 v235, 0x18c000, v233
	global_store_dwordx4 v235, v[20:23], s[18:19]
	v_add_u32_e32 v235, 0x1b8000, v233
	global_store_dwordx4 v235, v[16:19], s[18:19]
	v_add_u32_e32 v235, 0x1e4000, v233
	s_mov_b64 exec, s[62:63]
	global_store_dwordx4 v235, v[56:59], s[18:19]
	s_mov_b64 exec, s[8:9]
